# also setup2 H-init row loop: 24 loads per row issued together (v53 base: vcc-only transposes, no XCD remap)
# speedup vs baseline: 1.0029x; 1.0029x over previous
.LBB0_180:
	v_lshl_add_u64 v[38:39], v[40:41], 4, s[30:31]
	global_load_dwordx4 v[0:3], v[38:39], off
	s_and_b64 s[28:29], exec, s[28:29]
	s_cselect_b32 s22, s35, 0x6000
	s_lshl_b64 s[28:29], s[26:27], 13
	s_lshl_b64 s[30:31], s[26:27], 12
	s_cmpk_gt_i32 s12, 0x1fff
	s_cselect_b32 s22, s22, 0
	s_lshl_b32 s22, s22, 2
	v_lshl_add_u64 v[50:51], v[24:25], 0, s[28:29]
	s_add_u32 s28, s10, s22
	s_addc_u32 s29, s11, 0
	v_lshl_add_u64 v[34:35], v[12:13], 2, s[28:29]
	v_add_co_u32_e32 v30, vcc, s35, v34
	v_lshl_add_u64 v[28:29], v[26:27], 0, s[30:31]
	s_nop 0
	v_addc_co_u32_e32 v31, vcc, 0, v35, vcc
	v_lshl_add_u64 v[52:53], v[34:35], 0, s[24:25]
	v_add_co_u32_e32 v192, vcc, s38, v38
	v_addc_co_u32_e32 v193, vcc, 0, v39, vcc
	global_load_dwordx4 v[100:103], v[38:39], off offset:1024
	global_load_dwordx4 v[104:107], v[38:39], off offset:2048
	global_load_dwordx4 v[108:111], v[38:39], off offset:3072
	global_load_dwordx4 v[112:115], v[192:193], off
	global_load_dwordx4 v[116:119], v[192:193], off offset:1024
	global_load_dwordx4 v[120:123], v[192:193], off offset:2048
	global_load_dwordx4 v[124:127], v[192:193], off offset:3072
	global_load_dwordx4 v[128:131], v[14:15], off
	global_load_dwordx4 v[160:163], v[30:31], off offset:-4096
	global_load_dwordx4 v[132:135], v[14:15], off offset:1024
	global_load_dwordx4 v[164:167], v[52:53], off offset:1024
	global_load_dwordx4 v[136:139], v[14:15], off offset:2048
	global_load_dwordx4 v[168:171], v[52:53], off offset:2048
	global_load_dwordx4 v[140:143], v[14:15], off offset:3072
	global_load_dwordx4 v[172:175], v[52:53], off offset:3072
	global_load_dwordx4 v[144:147], v[16:17], off
	global_load_dwordx4 v[176:179], v[30:31], off
	global_load_dwordx4 v[148:151], v[18:19], off
	global_load_dwordx4 v[180:183], v[30:31], off offset:1024
	global_load_dwordx4 v[152:155], v[20:21], off
	global_load_dwordx4 v[184:187], v[30:31], off offset:2048
	global_load_dwordx4 v[156:159], v[22:23], off
	global_load_dwordx4 v[188:191], v[30:31], off offset:3072
	s_waitcnt vmcnt(23)
	global_store_dwordx4 v[50:51], v[0:3], off
	s_nop 1
	s_waitcnt vmcnt(16)
	v_mov_b32_e32 v4, v128
	v_mov_b32_e32 v5, v129
	v_mov_b32_e32 v6, v130
	v_mov_b32_e32 v7, v131
	s_nop 1
	s_waitcnt vmcnt(15)
	v_mov_b32_e32 v8, v160
	v_mov_b32_e32 v9, v161
	v_mov_b32_e32 v10, v162
	v_mov_b32_e32 v11, v163
	v_pk_mul_f32 v[6:7], v[2:3], v[6:7]
	v_pk_mul_f32 v[4:5], v[0:1], v[4:5]
	v_pk_add_f32 v[10:11], v[10:11], 1.0 op_sel_hi:[1,0]
	v_pk_add_f32 v[8:9], v[8:9], 1.0 op_sel_hi:[1,0]
	v_pk_mul_f32 v[6:7], v[6:7], v[10:11]
	v_pk_mul_f32 v[4:5], v[4:5], v[8:9]
	v_bfe_u32 v10, v6, 16, 1
	v_bfe_u32 v8, v4, 16, 1
	v_bfe_u32 v9, v5, 16, 1
	v_bfe_u32 v11, v7, 16, 1
	v_add3_u32 v4, v4, v8, s36
	v_add3_u32 v6, v6, v10, s36
	v_add3_u32 v5, v5, v9, s36
	v_add3_u32 v7, v7, v11, s36
	v_lshrrev_b32_e32 v4, 16, v4
	v_lshrrev_b32_e32 v6, 16, v6
	v_and_or_b32 v4, v5, s37, v4
	v_and_or_b32 v5, v7, s37, v6
	global_store_dwordx2 v[28:29], v[4:5], off
	s_nop 1
	s_waitcnt vmcnt(24)
	v_mov_b32_e32 v4, v100
	v_mov_b32_e32 v5, v101
	v_mov_b32_e32 v6, v102
	v_mov_b32_e32 v7, v103
	v_pk_mul_f32 v[2:3], v[2:3], v[2:3]
	v_pk_mul_f32 v[0:1], v[0:1], v[0:1]
	global_store_dwordx4 v[50:51], v[4:7], off offset:1024
	s_nop 1
	s_waitcnt vmcnt(16)
	v_mov_b32_e32 v8, v132
	v_mov_b32_e32 v9, v133
	v_mov_b32_e32 v10, v134
	v_mov_b32_e32 v11, v135
	s_nop 1
	s_waitcnt vmcnt(15)
	v_mov_b32_e32 v34, v164
	v_mov_b32_e32 v35, v165
	v_mov_b32_e32 v36, v166
	v_mov_b32_e32 v37, v167
	v_add_f32_e32 v0, v0, v1
	v_add_f32_e32 v1, v2, v3
	v_pk_mul_f32 v[2:3], v[4:5], v[4:5]
	v_pk_mul_f32 v[10:11], v[6:7], v[10:11]
	v_pk_mul_f32 v[8:9], v[4:5], v[8:9]
	v_pk_add_f32 v[36:37], v[36:37], 1.0 op_sel_hi:[1,0]
	v_pk_add_f32 v[34:35], v[34:35], 1.0 op_sel_hi:[1,0]
	v_pk_mul_f32 v[10:11], v[10:11], v[36:37]
	v_pk_mul_f32 v[8:9], v[8:9], v[34:35]
	v_bfe_u32 v36, v10, 16, 1
	v_bfe_u32 v34, v8, 16, 1
	v_bfe_u32 v35, v9, 16, 1
	v_bfe_u32 v37, v11, 16, 1
	v_add3_u32 v8, v8, v34, s36
	v_add3_u32 v10, v10, v36, s36
	v_add3_u32 v9, v9, v35, s36
	v_add3_u32 v11, v11, v37, s36
	v_lshrrev_b32_e32 v8, 16, v8
	v_lshrrev_b32_e32 v10, 16, v10
	v_and_or_b32 v8, v9, s37, v8
	v_and_or_b32 v9, v11, s37, v10
	global_store_dwordx2 v[28:29], v[8:9], off offset:512
	s_nop 1
	s_waitcnt vmcnt(25)
	v_mov_b32_e32 v8, v104
	v_mov_b32_e32 v9, v105
	v_mov_b32_e32 v10, v106
	v_mov_b32_e32 v11, v107
	v_add_f32_e32 v2, v2, v3
	global_store_dwordx4 v[50:51], v[8:11], off offset:2048
	s_nop 1
	s_waitcnt vmcnt(16)
	v_mov_b32_e32 v34, v136
	v_mov_b32_e32 v35, v137
	v_mov_b32_e32 v36, v138
	v_mov_b32_e32 v37, v139
	s_nop 1
	s_waitcnt vmcnt(15)
	v_mov_b32_e32 v42, v168
	v_mov_b32_e32 v43, v169
	v_mov_b32_e32 v44, v170
	v_mov_b32_e32 v45, v171
	v_pk_mul_f32 v[36:37], v[10:11], v[36:37]
	v_pk_mul_f32 v[34:35], v[8:9], v[34:35]
	v_pk_add_f32 v[44:45], v[44:45], 1.0 op_sel_hi:[1,0]
	v_pk_add_f32 v[42:43], v[42:43], 1.0 op_sel_hi:[1,0]
	v_pk_mul_f32 v[36:37], v[36:37], v[44:45]
	v_pk_mul_f32 v[34:35], v[34:35], v[42:43]
	v_bfe_u32 v44, v36, 16, 1
	v_bfe_u32 v42, v34, 16, 1
	v_bfe_u32 v43, v35, 16, 1
	v_bfe_u32 v45, v37, 16, 1
	v_add3_u32 v34, v34, v42, s36
	v_add3_u32 v36, v36, v44, s36
	v_add3_u32 v35, v35, v43, s36
	v_add3_u32 v37, v37, v45, s36
	v_lshrrev_b32_e32 v34, 16, v34
	v_lshrrev_b32_e32 v36, 16, v36
	v_and_or_b32 v34, v35, s37, v34
	v_and_or_b32 v35, v37, s37, v36
	global_store_dwordx2 v[28:29], v[34:35], off offset:1024
	s_nop 1
	s_waitcnt vmcnt(26)
	v_mov_b32_e32 v34, v108
	v_mov_b32_e32 v35, v109
	v_mov_b32_e32 v36, v110
	v_mov_b32_e32 v37, v111
	v_add_co_u32_e32 v38, vcc, s38, v38
	global_store_dwordx4 v[50:51], v[34:37], off offset:3072
	s_nop 1
	s_waitcnt vmcnt(16)
	v_mov_b32_e32 v42, v140
	v_mov_b32_e32 v43, v141
	v_mov_b32_e32 v44, v142
	v_mov_b32_e32 v45, v143
	s_nop 1
	s_waitcnt vmcnt(15)
	v_mov_b32_e32 v46, v172
	v_mov_b32_e32 v47, v173
	v_mov_b32_e32 v48, v174
	v_mov_b32_e32 v49, v175
	v_addc_co_u32_e32 v39, vcc, 0, v39, vcc
	v_add_co_u32_e32 v62, vcc, s38, v50
	v_pk_mul_f32 v[44:45], v[36:37], v[44:45]
	v_pk_mul_f32 v[42:43], v[34:35], v[42:43]
	v_pk_add_f32 v[48:49], v[48:49], 1.0 op_sel_hi:[1,0]
	v_pk_add_f32 v[46:47], v[46:47], 1.0 op_sel_hi:[1,0]
	v_pk_mul_f32 v[44:45], v[44:45], v[48:49]
	v_pk_mul_f32 v[42:43], v[42:43], v[46:47]
	v_bfe_u32 v48, v44, 16, 1
	v_bfe_u32 v46, v42, 16, 1
	v_bfe_u32 v47, v43, 16, 1
	v_bfe_u32 v49, v45, 16, 1
	v_add3_u32 v42, v42, v46, s36
	v_add3_u32 v44, v44, v48, s36
	v_add3_u32 v43, v43, v47, s36
	v_add3_u32 v45, v45, v49, s36
	v_lshrrev_b32_e32 v42, 16, v42
	v_lshrrev_b32_e32 v44, 16, v44
	v_and_or_b32 v42, v43, s37, v42
	v_and_or_b32 v43, v45, s37, v44
	global_store_dwordx2 v[28:29], v[42:43], off offset:1536
	s_nop 1
	s_waitcnt vmcnt(27)
	v_mov_b32_e32 v42, v112
	v_mov_b32_e32 v43, v113
	v_mov_b32_e32 v44, v114
	v_mov_b32_e32 v45, v115
	v_addc_co_u32_e32 v63, vcc, 0, v51, vcc
	global_store_dwordx4 v[62:63], v[42:45], off
	s_nop 1
	s_waitcnt vmcnt(16)
	v_mov_b32_e32 v46, v144
	v_mov_b32_e32 v47, v145
	v_mov_b32_e32 v48, v146
	v_mov_b32_e32 v49, v147
	s_nop 1
	s_waitcnt vmcnt(15)
	v_mov_b32_e32 v50, v176
	v_mov_b32_e32 v51, v177
	v_mov_b32_e32 v52, v178
	v_mov_b32_e32 v53, v179
	v_pk_mul_f32 v[48:49], v[44:45], v[48:49]
	v_pk_mul_f32 v[46:47], v[42:43], v[46:47]
	v_pk_add_f32 v[52:53], v[52:53], 1.0 op_sel_hi:[1,0]
	v_pk_add_f32 v[50:51], v[50:51], 1.0 op_sel_hi:[1,0]
	v_pk_mul_f32 v[48:49], v[48:49], v[52:53]
	v_pk_mul_f32 v[46:47], v[46:47], v[50:51]
	v_bfe_u32 v52, v48, 16, 1
	v_bfe_u32 v50, v46, 16, 1
	v_bfe_u32 v51, v47, 16, 1
	v_bfe_u32 v53, v49, 16, 1
	v_add3_u32 v46, v46, v50, s36
	v_add3_u32 v48, v48, v52, s36
	v_add3_u32 v47, v47, v51, s36
	v_add3_u32 v49, v49, v53, s36
	v_lshrrev_b32_e32 v46, 16, v46
	v_lshrrev_b32_e32 v48, 16, v48
	v_and_or_b32 v46, v47, s37, v46
	v_and_or_b32 v47, v49, s37, v48
	global_store_dwordx2 v[28:29], v[46:47], off offset:2048
	s_nop 1
	s_waitcnt vmcnt(28)
	v_mov_b32_e32 v46, v116
	v_mov_b32_e32 v47, v117
	v_mov_b32_e32 v48, v118
	v_mov_b32_e32 v49, v119
	global_store_dwordx4 v[62:63], v[46:49], off offset:1024
	s_nop 1
	s_waitcnt vmcnt(16)
	v_mov_b32_e32 v50, v148
	v_mov_b32_e32 v51, v149
	v_mov_b32_e32 v52, v150
	v_mov_b32_e32 v53, v151
	s_nop 1
	s_waitcnt vmcnt(15)
	v_mov_b32_e32 v54, v180
	v_mov_b32_e32 v55, v181
	v_mov_b32_e32 v56, v182
	v_mov_b32_e32 v57, v183
	v_pk_mul_f32 v[52:53], v[48:49], v[52:53]
	v_pk_mul_f32 v[50:51], v[46:47], v[50:51]
	v_pk_add_f32 v[56:57], v[56:57], 1.0 op_sel_hi:[1,0]
	v_pk_add_f32 v[54:55], v[54:55], 1.0 op_sel_hi:[1,0]
	v_pk_mul_f32 v[52:53], v[52:53], v[56:57]
	v_pk_mul_f32 v[50:51], v[50:51], v[54:55]
	v_bfe_u32 v56, v52, 16, 1
	v_bfe_u32 v54, v50, 16, 1
	v_bfe_u32 v55, v51, 16, 1
	v_bfe_u32 v57, v53, 16, 1
	v_add3_u32 v50, v50, v54, s36
	v_add3_u32 v52, v52, v56, s36
	v_add3_u32 v51, v51, v55, s36
	v_add3_u32 v53, v53, v57, s36
	v_lshrrev_b32_e32 v50, 16, v50
	v_lshrrev_b32_e32 v52, 16, v52
	v_and_or_b32 v50, v51, s37, v50
	v_and_or_b32 v51, v53, s37, v52
	global_store_dwordx2 v[28:29], v[50:51], off offset:2560
	s_nop 1
	s_waitcnt vmcnt(29)
	v_mov_b32_e32 v50, v120
	v_mov_b32_e32 v51, v121
	v_mov_b32_e32 v52, v122
	v_mov_b32_e32 v53, v123
	global_store_dwordx4 v[62:63], v[50:53], off offset:2048
	s_nop 1
	s_waitcnt vmcnt(16)
	v_mov_b32_e32 v54, v152
	v_mov_b32_e32 v55, v153
	v_mov_b32_e32 v56, v154
	v_mov_b32_e32 v57, v155
	s_nop 1
	s_waitcnt vmcnt(15)
	v_mov_b32_e32 v58, v184
	v_mov_b32_e32 v59, v185
	v_mov_b32_e32 v60, v186
	v_mov_b32_e32 v61, v187
	v_pk_mul_f32 v[56:57], v[52:53], v[56:57]
	v_pk_mul_f32 v[54:55], v[50:51], v[54:55]
	v_pk_add_f32 v[60:61], v[60:61], 1.0 op_sel_hi:[1,0]
	v_pk_add_f32 v[58:59], v[58:59], 1.0 op_sel_hi:[1,0]
	v_pk_mul_f32 v[56:57], v[56:57], v[60:61]
	v_pk_mul_f32 v[54:55], v[54:55], v[58:59]
	v_bfe_u32 v60, v56, 16, 1
	v_bfe_u32 v58, v54, 16, 1
	v_bfe_u32 v59, v55, 16, 1
	v_bfe_u32 v61, v57, 16, 1
	v_add3_u32 v54, v54, v58, s36
	v_add3_u32 v56, v56, v60, s36
	v_add3_u32 v55, v55, v59, s36
	v_add3_u32 v57, v57, v61, s36
	v_lshrrev_b32_e32 v54, 16, v54
	v_lshrrev_b32_e32 v56, 16, v56
	v_and_or_b32 v54, v55, s37, v54
	v_and_or_b32 v55, v57, s37, v56
	global_store_dwordx2 v[28:29], v[54:55], off offset:3072
	s_nop 1
	s_waitcnt vmcnt(30)
	v_mov_b32_e32 v54, v124
	v_mov_b32_e32 v55, v125
	v_mov_b32_e32 v56, v126
	v_mov_b32_e32 v57, v127
	global_store_dwordx4 v[62:63], v[54:57], off offset:3072
	s_nop 1
	s_waitcnt vmcnt(16)
	v_mov_b32_e32 v58, v156
	v_mov_b32_e32 v59, v157
	v_mov_b32_e32 v60, v158
	v_mov_b32_e32 v61, v159
	s_nop 0
	s_nop 1
	s_waitcnt vmcnt(15)
	v_mov_b32_e32 v62, v188
	v_mov_b32_e32 v63, v189
	v_mov_b32_e32 v64, v190
	v_mov_b32_e32 v65, v191
	v_add_f32_e32 v30, v0, v1
	v_pk_mul_f32 v[0:1], v[6:7], v[6:7]
	v_pk_add_f32 v[6:7], v[62:63], 1.0 op_sel_hi:[1,0]
	v_add_f32_e32 v0, v0, v1
	v_add_f32_e32 v0, v2, v0
	v_add_f32_e32 v4, v30, v0
	v_pk_mul_f32 v[0:1], v[10:11], v[10:11]
	v_pk_mul_f32 v[2:3], v[8:9], v[8:9]
	v_add_f32_e32 v0, v0, v1
	v_add_f32_e32 v2, v2, v3
	v_add_f32_e32 v0, v2, v0
	v_add_f32_e32 v4, v4, v0
	v_pk_mul_f32 v[0:1], v[36:37], v[36:37]
	v_pk_mul_f32 v[2:3], v[34:35], v[34:35]
	v_add_f32_e32 v0, v0, v1
	v_add_f32_e32 v2, v2, v3
	v_add_f32_e32 v0, v2, v0
	v_add_f32_e32 v4, v4, v0
	v_pk_mul_f32 v[0:1], v[44:45], v[44:45]
	v_pk_mul_f32 v[2:3], v[42:43], v[42:43]
	v_add_f32_e32 v0, v0, v1
	v_add_f32_e32 v2, v2, v3
	v_add_f32_e32 v0, v2, v0
	v_add_f32_e32 v4, v4, v0
	v_pk_mul_f32 v[0:1], v[48:49], v[48:49]
	v_pk_mul_f32 v[2:3], v[46:47], v[46:47]
	v_add_f32_e32 v0, v0, v1
	v_add_f32_e32 v2, v2, v3
	v_add_f32_e32 v0, v2, v0
	v_add_f32_e32 v4, v4, v0
	v_pk_mul_f32 v[0:1], v[52:53], v[52:53]
	v_pk_mul_f32 v[2:3], v[50:51], v[50:51]
	v_add_f32_e32 v0, v0, v1
	v_add_f32_e32 v2, v2, v3
	v_add_f32_e32 v0, v2, v0
	v_add_f32_e32 v4, v4, v0
	v_pk_mul_f32 v[0:1], v[56:57], v[56:57]
	v_pk_mul_f32 v[2:3], v[54:55], v[54:55]
	v_add_f32_e32 v0, v0, v1
	v_add_f32_e32 v2, v2, v3
	v_add_f32_e32 v0, v2, v0
	v_add_f32_e32 v0, v4, v0
	v_pk_mul_f32 v[2:3], v[54:55], v[58:59]
	v_pk_add_f32 v[4:5], v[64:65], 1.0 op_sel_hi:[1,0]
	v_add_f32_dpp v0, v0, v0 quad_perm:[1,0,3,2] row_mask:0xf bank_mask:0xf bound_ctrl:1
	v_pk_mul_f32 v[2:3], v[2:3], v[6:7]
	s_nop 0
	v_add_f32_dpp v0, v0, v0 quad_perm:[2,3,0,1] row_mask:0xf bank_mask:0xf bound_ctrl:1
	s_nop 1
	v_add_f32_dpp v0, v0, v0 row_half_mirror row_mask:0xf bank_mask:0xf bound_ctrl:1
	s_nop 1
	v_add_f32_dpp v8, v0, v0 row_mirror row_mask:0xf bank_mask:0xf bound_ctrl:1
	v_pk_mul_f32 v[0:1], v[56:57], v[60:61]
	v_readlane_b32 s28, v8, 0
	v_pk_mul_f32 v[0:1], v[0:1], v[4:5]
	v_bfe_u32 v4, v2, 16, 1
	v_bfe_u32 v6, v0, 16, 1
	v_bfe_u32 v5, v3, 16, 1
	v_bfe_u32 v7, v1, 16, 1
	v_add3_u32 v2, v2, v4, s36
	v_add3_u32 v0, v0, v6, s36
	v_add3_u32 v3, v3, v5, s36
	v_add3_u32 v1, v1, v7, s36
	v_lshrrev_b32_e32 v2, 16, v2
	v_lshrrev_b32_e32 v4, 16, v0
	v_readlane_b32 s22, v8, 16
	v_readlane_b32 s29, v8, 32
	v_and_or_b32 v0, v3, s37, v2
	v_and_or_b32 v1, v1, s37, v4
	v_readlane_b32 s39, v8, 48
	global_store_dwordx2 v[28:29], v[0:1], off offset:3584
	s_and_saveexec_b64 s[30:31], s[4:5]
	s_cbranch_execz .LBB0_177
	v_mov_b32_e32 v0, s22
	v_mov_b32_e32 v1, s39
	v_pk_add_f32 v[0:1], s[28:29], v[0:1]
	s_lshl_b64 s[26:27], s[26:27], 2
	v_add_f32_e32 v0, v0, v1
	v_fmamk_f32 v0, v0, 0x3a000000, v32
	v_rsq_f32_e32 v0, v0
	s_add_u32 s26, s33, s26
	s_addc_u32 s27, s34, s27
	global_store_dword v33, v0, s[26:27]
	s_branch .LBB0_177
